# v66 + G1 register-only bf16 epilogue (permlane transposes) with the next tile's first half-chunks issued at its start
# baseline (speedup 1.0000x reference)
.LBB1_1172:
	s_and_b64 vcc, exec, s[38:39]
	s_cbranch_vccz .LBB1_1482
	s_mov_b32 s59, 0
	s_mov_b32 s2, 0
	s_branch .LBB1_1176

.LBB1_1179:
	v_mov_b32_e32 v138, v162
	s_lshl_b32 s6, s5, 8
	v_readfirstlane_b32 s7, v138
	v_lshrrev_b32_e32 v0, 3, v138
	v_and_b32_e32 v0, 6, v0
	s_movk_i32 s11, 0x78
	s_and_b32 s9, s7, 0xffffffc0
	s_waitcnt lgkmcnt(0)
	v_bfe_u32 v2, v138, 2, 4
	v_lshrrev_b32_e64 v0, v0, s11
	s_add_i32 s9, s9, s6
	v_xor_b32_e32 v3, v0, v138
	v_or_b32_e32 v0, s9, v2
	v_ashrrev_i32_e32 v1, 31, v0
	v_lshlrev_b64 v[0:1], 11, v[0:1]
	v_lshlrev_b32_e32 v3, 4, v3
	s_lshl_b32 s30, s4, 7
	v_lshl_add_u64 v[0:1], s[74:75], 0, v[0:1]
	v_and_b32_e32 v128, 48, v3
	s_load_dwordx16 s[80:95], s[0:1], 0xc0
	s_ashr_i32 s8, s7, 6
	v_lshl_add_u64 v[130:131], v[0:1], 0, v[128:129]
	v_or_b32_e32 v0, s30, v2
	v_lshl_add_u32 v0, s8, 5, v0
	v_ashrrev_i32_e32 v1, 31, v0
	v_lshlrev_b64 v[0:1], 11, v[0:1]
	s_waitcnt lgkmcnt(0)
	v_lshl_add_u64 v[0:1], s[84:85], 0, v[0:1]
	v_lshl_add_u64 v[132:133], v[0:1], 0, v[128:129]
	v_lshrrev_b32_e32 v0, 1, v138
	v_and_b32_e32 v0, 6, v0
	v_bfe_u32 v140, v138, 4, 2
	s_lshl_b32 s9, s8, 12
	v_lshrrev_b32_e64 v0, v0, s11
	v_and_b32_e32 v139, 15, v138
	s_lshl_b32 s10, s8, 11
	s_and_b32 s8, s7, 0xffffff80
	v_bitop3_b32 v0, v0, v140, 3 bitop3:0x6c
	s_and_b32 s7, s7, 64
	s_add_i32 s11, s9, 16
	v_lshlrev_b32_e32 v134, 4, v0
	v_or_b32_e32 v0, s7, v139
	s_mov_b32 m0, s11
	v_lshlrev_b32_e32 v135, 6, v0
	s_barrier
	v_lshl_add_u64 v[0:1], v[130:131], 0, s[34:35]
	s_add_i32 m0, s11, 0x400
	s_mov_b64 s[12:13], 0x10000
	v_lshl_add_u64 v[0:1], v[130:131], 0, s[12:13]
	s_add_i32 m0, s11, 0x800
	s_mov_b64 s[12:13], 0x18000
	v_lshl_add_u64 v[0:1], v[130:131], 0, s[12:13]
	s_add_i32 m0, s11, 0xc00
	s_sub_i32 s12, s11, s10
	s_add_i32 m0, s12, 0x4000
	v_lshl_add_u64 v[0:1], v[132:133], 0, s[34:35]
	s_add_i32 m0, s12, 0x4400
	s_mov_b64 s[14:15], 0x8040
	v_lshl_add_u64 v[0:1], v[130:131], 0, 64
	s_add_i32 m0, s11, 0x6000
	s_mov_b64 s[16:17], 0x10040
	v_lshl_add_u64 v[0:1], v[130:131], 0, s[14:15]
	s_add_i32 m0, s11, 0x6400
	v_or_b32_e32 v141, s8, v139
	v_lshl_add_u64 v[0:1], v[130:131], 0, s[16:17]
	s_add_i32 m0, s11, 0x6800
	s_mov_b64 s[16:17], 0x18040
	v_lshl_add_u64 v[0:1], v[130:131], 0, s[16:17]
	s_add_i32 m0, s11, 0x6c00
	v_lshlrev_b32_e32 v128, 6, v141
	v_lshl_add_u64 v[0:1], v[132:133], 0, 64
	s_add_i32 m0, s12, 0xa000
	s_mov_b32 s11, 0
	v_lshl_add_u64 v[0:1], v[132:133], 0, s[14:15]
	s_add_i32 m0, s12, 0xa400
	s_mov_b32 s12, 0
	v_mov_b32_e32 v0, 0
	v_mov_b32_e32 v1, v0
	v_mov_b32_e32 v2, v0
	v_mov_b32_e32 v3, v0
	v_mov_b32_e32 v4, v0
	v_mov_b32_e32 v5, v0
	v_mov_b32_e32 v6, v0
	v_mov_b32_e32 v7, v0
	v_mov_b32_e32 v8, v0
	v_mov_b32_e32 v9, v0
	v_mov_b32_e32 v10, v0
	v_mov_b32_e32 v11, v0
	v_mov_b32_e32 v12, v0
	v_mov_b32_e32 v13, v0
	v_mov_b32_e32 v14, v0
	v_mov_b32_e32 v15, v0
	v_mov_b32_e32 v16, v0
	v_mov_b32_e32 v17, v0
	v_mov_b32_e32 v18, v0
	v_mov_b32_e32 v19, v0
	v_mov_b32_e32 v20, v0
	v_mov_b32_e32 v21, v0
	v_mov_b32_e32 v22, v0
	v_mov_b32_e32 v23, v0
	v_mov_b32_e32 v24, v0
	v_mov_b32_e32 v25, v0
	v_mov_b32_e32 v26, v0
	v_mov_b32_e32 v27, v0
	v_mov_b32_e32 v28, v0
	v_mov_b32_e32 v29, v0
	v_mov_b32_e32 v30, v0
	v_mov_b32_e32 v31, v0
	v_mov_b32_e32 v32, v0
	v_mov_b32_e32 v33, v0
	v_mov_b32_e32 v34, v0
	v_mov_b32_e32 v35, v0
	v_mov_b32_e32 v36, v0
	v_mov_b32_e32 v37, v0
	v_mov_b32_e32 v38, v0
	v_mov_b32_e32 v39, v0
	v_mov_b32_e32 v40, v0
	v_mov_b32_e32 v41, v0
	v_mov_b32_e32 v42, v0
	v_mov_b32_e32 v43, v0
	v_mov_b32_e32 v44, v0
	v_mov_b32_e32 v45, v0
	v_mov_b32_e32 v46, v0
	v_mov_b32_e32 v47, v0
	v_mov_b32_e32 v48, v0
	v_mov_b32_e32 v49, v0
	v_mov_b32_e32 v50, v0
	v_mov_b32_e32 v51, v0
	v_mov_b32_e32 v68, v0
	v_mov_b32_e32 v69, v0
	v_mov_b32_e32 v70, v0
	v_mov_b32_e32 v71, v0
	v_mov_b32_e32 v72, v0
	v_mov_b32_e32 v73, v0
	v_mov_b32_e32 v74, v0
	v_mov_b32_e32 v75, v0
	v_mov_b32_e32 v76, v0
	v_mov_b32_e32 v77, v0
	v_mov_b32_e32 v78, v0
	v_mov_b32_e32 v79, v0
	v_mov_b32_e32 v80, v0
	v_mov_b32_e32 v81, v0
	v_mov_b32_e32 v82, v0
	v_mov_b32_e32 v83, v0
	v_mov_b32_e32 v84, v0
	v_mov_b32_e32 v85, v0
	v_mov_b32_e32 v86, v0
	v_mov_b32_e32 v87, v0
	v_mov_b32_e32 v88, v0
	v_mov_b32_e32 v89, v0
	v_mov_b32_e32 v90, v0
	v_mov_b32_e32 v91, v0
	v_mov_b32_e32 v92, v0
	v_mov_b32_e32 v93, v0
	v_mov_b32_e32 v94, v0
	v_mov_b32_e32 v95, v0
	v_mov_b32_e32 v96, v0
	v_mov_b32_e32 v97, v0
	v_mov_b32_e32 v98, v0
	v_mov_b32_e32 v99, v0
	v_mov_b32_e32 v100, v0
	v_mov_b32_e32 v101, v0
	v_mov_b32_e32 v102, v0
	v_mov_b32_e32 v103, v0
	v_mov_b32_e32 v104, v0
	v_mov_b32_e32 v105, v0
	v_mov_b32_e32 v106, v0
	v_mov_b32_e32 v107, v0
	v_mov_b32_e32 v108, v0
	v_mov_b32_e32 v109, v0
	v_mov_b32_e32 v110, v0
	v_mov_b32_e32 v111, v0
	v_mov_b32_e32 v112, v0
	v_mov_b32_e32 v113, v0
	v_mov_b32_e32 v114, v0
	v_mov_b32_e32 v115, v0
	v_mov_b32_e32 v116, v0
	v_mov_b32_e32 v117, v0
	v_mov_b32_e32 v118, v0
	v_mov_b32_e32 v119, v0
	v_mov_b32_e32 v120, v0
	v_mov_b32_e32 v121, v0
	v_mov_b32_e32 v122, v0
	v_mov_b32_e32 v123, v0
	v_mov_b32_e32 v124, v0
	v_mov_b32_e32 v125, v0
	v_mov_b32_e32 v126, v0
	v_mov_b32_e32 v127, v0
	v_mov_b32_e32 v60, v0
	v_mov_b32_e32 v61, v0
	v_mov_b32_e32 v62, v0
	v_mov_b32_e32 v63, v0
	v_mov_b32_e32 v64, v0
	v_mov_b32_e32 v65, v0
	v_mov_b32_e32 v66, v0
	v_mov_b32_e32 v67, v0
	v_mov_b32_e32 v52, v0
	v_mov_b32_e32 v53, v0
	v_mov_b32_e32 v54, v0
	v_mov_b32_e32 v55, v0
	v_mov_b32_e32 v56, v0
	v_mov_b32_e32 v57, v0
	v_mov_b32_e32 v58, v0
	v_mov_b32_e32 v59, v0
	s_mov_b64 s[16:17], 0x10080
	v_and_b32_e32 v204, 15, v168
	v_lshrrev_b32_e32 v205, 4, v168
	v_bfe_u32 v206, v168, 1, 3
	v_xor_b32_e32 v205, v205, v206
	v_lshlrev_b32_e32 v205, 4, v205
	v_readfirstlane_b32 s15, v162
	v_readfirstlane_b32 s18, v130
	v_readfirstlane_b32 s19, v131
	v_readfirstlane_b32 s28, v132
	v_readfirstlane_b32 s29, v133
	s_lshr_b32 s15, s15, 6
	s_lshl_b32 s54, s15, 12
	s_lshr_b32 s41, s15, 1
	s_and_b32 s42, s15, 1
	v_lshl_add_u32 v206, s41, 6, v204
	v_lshl_add_u32 v196, v206, 7, v205
	v_xor_b32_e32 v197, 64, v196
	v_lshl_add_u32 v206, s42, 6, v204
	v_lshl_add_u32 v198, v206, 7, v205
	v_xor_b32_e32 v199, 64, v198
	v_add_u32_e32 v198, 0xc010, v198
	v_add_u32_e32 v199, 0xc010, v199
	v_lshrrev_b32_e32 v206, 3, v168
	v_and_b32_e32 v207, 7, v168
	v_lshrrev_b32_e32 v204, 1, v206
	v_xor_b32_e32 v207, v207, v204
	v_lshlrev_b32_e32 v207, 4, v207
	v_lshl_add_u32 v200, v206, 11, v207
	v_xor_b32_e32 v201, 64, v200
	s_lshl_b32 s42, s42, 16
	s_sub_u32 s18, s18, s42
	s_subb_u32 s19, s19, 0
	s_cmp_eq_u32 s59, 1
	s_cbranch_scc1 .Lflpf_skip
	s_add_i32 s41, s54, 16
	s_add_i32 m0, s41, 0x0
	s_nop 0
	global_load_lds_dwordx4 v200, s[18:19]
	s_add_i32 m0, s41, 0x400
	s_add_u32 s52, s18, 0x4000
	s_addc_u32 s53, s19, 0
	global_load_lds_dwordx4 v201, s[52:53]
	s_add_i32 m0, s41, 0x800
	s_add_u32 s52, s18, 0x8000
	s_addc_u32 s53, s19, 0
	global_load_lds_dwordx4 v200, s[52:53]
	s_add_i32 m0, s41, 0xc00
	s_add_u32 s52, s18, 0xc000
	s_addc_u32 s53, s19, 0
	global_load_lds_dwordx4 v201, s[52:53]
	s_add_i32 m0, s54, 0xc010
	s_nop 0
	global_load_lds_dwordx4 v200, s[28:29]
	s_add_i32 m0, s54, 0xc410
	s_add_u32 s52, s28, 0x4000
	s_addc_u32 s53, s29, 0
	global_load_lds_dwordx4 v201, s[52:53]
	s_add_i32 m0, s54, 0xc810
	s_add_u32 s52, s28, 0x8000
	s_addc_u32 s53, s29, 0
	global_load_lds_dwordx4 v200, s[52:53]
	s_add_i32 m0, s54, 0xcc10
	s_add_u32 s52, s28, 0xc000
	s_addc_u32 s53, s29, 0
	global_load_lds_dwordx4 v201, s[52:53]
	s_add_u32 s50, s18, 0x20000
	s_addc_u32 s51, s19, 0
	s_add_i32 m0, s41, 0x4000
	s_nop 0
	global_load_lds_dwordx4 v200, s[50:51]
	s_add_i32 m0, s41, 0x4400
	s_add_u32 s52, s50, 0x4000
	s_addc_u32 s53, s51, 0
	global_load_lds_dwordx4 v201, s[52:53]
	s_add_i32 m0, s41, 0x4800
	s_add_u32 s52, s50, 0x8000
	s_addc_u32 s53, s51, 0
	global_load_lds_dwordx4 v200, s[52:53]
	s_add_i32 m0, s41, 0x4c00
	s_add_u32 s52, s50, 0xc000
	s_addc_u32 s53, s51, 0
	global_load_lds_dwordx4 v201, s[52:53]
.Lflpf_skip:
	s_mov_b32 s59, 0
	s_mov_b32 s13, 0
	s_mov_b32 s14, 0
	s_setprio 1

.LBB1_1291:
	s_and_b64 vcc, exec, s[38:39]
	s_cbranch_vccz .LBB1_1174
	v_readlane_b32 s13, v242, 0
	s_add_i32 s15, s2, 1
	s_lshl_b32 s15, s15, 3
	s_and_b32 s41, s13, 7
	s_or_b32 s15, s15, s41
	s_mul_i32 s15, s15, s55
	s_lshr_b32 s13, s13, 3
	s_add_i32 s15, s15, s13
	s_cmp_lt_u32 s15, 0xfff
	s_cselect_b32 s59, 1, 0
	s_cbranch_scc0 .Lflpf_none
	s_mul_i32 s41, s15, 2017
	s_lshr_b32 s41, s41, 20
	s_lshl_b32 s42, s41, 3
	s_sub_i32 s43, 63, s42
	s_min_u32 s43, s43, 8
	s_mul_i32 s46, s41, 520
	s_sub_i32 s46, s15, s46
	s_lshr_b32 s47, s46, 3
	s_mul_i32 s13, s46, 293
	s_lshr_b32 s13, s13, 11
	s_cmp_eq_u32 s43, 8
	s_cselect_b32 s47, s47, s13
	s_mul_i32 s13, s47, s43
	s_sub_i32 s13, s46, s13
	s_add_i32 s42, s42, s13
	s_lshl_b32 s42, s42, 8
	s_sub_i32 s42, s42, s6
	s_lshl_b32 s46, s47, 7
	s_sub_i32 s46, s46, s30
	s_ashr_i32 s43, s42, 31
	s_lshl_b64 s[42:43], s[42:43], 11
	s_add_u32 s50, s18, s42
	s_addc_u32 s51, s19, s43
	s_ashr_i32 s47, s46, 31
	s_lshl_b64 s[46:47], s[46:47], 11
	s_add_u32 s52, s28, s46
	s_addc_u32 s53, s29, s47
	s_add_u32 s12, s50, 0x20000
	s_addc_u32 s13, s51, 0
	s_add_i32 m0, s54, 0x10
	s_nop 0
	global_load_lds_dwordx4 v200, s[50:51]
	s_add_i32 m0, s54, 0x410
	s_add_u32 s14, s50, 0x4000
	s_addc_u32 s15, s51, 0
	global_load_lds_dwordx4 v201, s[14:15]
	s_add_i32 m0, s54, 0x810
	s_add_u32 s14, s50, 0x8000
	s_addc_u32 s15, s51, 0
	global_load_lds_dwordx4 v200, s[14:15]
	s_add_i32 m0, s54, 0xc10
	s_add_u32 s14, s50, 0xc000
	s_addc_u32 s15, s51, 0
	global_load_lds_dwordx4 v201, s[14:15]
	s_add_i32 m0, s54, 0xc010
	s_nop 0
	global_load_lds_dwordx4 v200, s[52:53]
	s_add_i32 m0, s54, 0xc410
	s_add_u32 s14, s52, 0x4000
	s_addc_u32 s15, s53, 0
	global_load_lds_dwordx4 v201, s[14:15]
	s_add_i32 m0, s54, 0xc810
	s_add_u32 s14, s52, 0x8000
	s_addc_u32 s15, s53, 0
	global_load_lds_dwordx4 v200, s[14:15]
	s_add_i32 m0, s54, 0xcc10
	s_add_u32 s14, s52, 0xc000
	s_addc_u32 s15, s53, 0
	global_load_lds_dwordx4 v201, s[14:15]
	s_add_i32 m0, s54, 0x4010
	s_nop 0
	global_load_lds_dwordx4 v200, s[12:13]
	s_add_i32 m0, s54, 0x4410
	s_add_u32 s14, s12, 0x4000
	s_addc_u32 s15, s13, 0
	global_load_lds_dwordx4 v201, s[14:15]
	s_add_i32 m0, s54, 0x4810
	s_add_u32 s14, s12, 0x8000
	s_addc_u32 s15, s13, 0
	global_load_lds_dwordx4 v200, s[14:15]
	s_add_i32 m0, s54, 0x4c10
	s_add_u32 s14, s12, 0xc000
	s_addc_u32 s15, s13, 0
	global_load_lds_dwordx4 v201, s[14:15]
.Lflpf_none:
	v_and_b32_e32 v204, 15, v168
	v_lshrrev_b32_e32 v205, 4, v168
	v_readfirstlane_b32 s8, v162
	s_lshr_b32 s8, s8, 6
	s_lshr_b32 s9, s8, 1
	s_and_b32 s8, s8, 1
	s_lshl_b32 s9, s9, 7
	s_add_i32 s9, s9, s6
	s_lshl_b32 s8, s8, 6
	s_add_i32 s8, s8, s30
	v_add_u32_e32 v204, s9, v204
	v_lshlrev_b32_e32 v204, 14, v204
	v_lshl_add_u32 v205, v205, 4, s8
	v_lshl_add_u32 v204, v205, 1, v204
	s_mov_b32 s10, s76
	s_mov_b32 s11, s77
	v_cvt_pk_bf16_f32 v148, v124, v125
	v_cvt_pk_bf16_f32 v149, v126, v127
	v_cvt_pk_bf16_f32 v150, v120, v121
	v_cvt_pk_bf16_f32 v151, v122, v123
	v_cvt_pk_bf16_f32 v152, v116, v117
	v_cvt_pk_bf16_f32 v153, v118, v119
	v_cvt_pk_bf16_f32 v154, v112, v113
	v_cvt_pk_bf16_f32 v155, v114, v115
	s_nop 1
	v_permlane32_swap_b32_e32 v148, v152
	v_permlane32_swap_b32_e32 v149, v153
	v_permlane32_swap_b32_e32 v150, v154
	v_permlane32_swap_b32_e32 v151, v155
	s_nop 0
	v_permlane16_swap_b32_e32 v148, v150
	v_permlane16_swap_b32_e32 v149, v151
	v_permlane16_swap_b32_e32 v152, v154
	v_permlane16_swap_b32_e32 v153, v155
	s_nop 1
	global_store_dwordx4 v204, v[148:151], s[10:11]
	global_store_dwordx4 v204, v[152:155], s[10:11] offset:16
	s_add_u32 s10, s76, 0x40000
	s_addc_u32 s11, s77, 0
	v_cvt_pk_bf16_f32 v188, v108, v109
	v_cvt_pk_bf16_f32 v189, v110, v111
	v_cvt_pk_bf16_f32 v190, v104, v105
	v_cvt_pk_bf16_f32 v191, v106, v107
	v_cvt_pk_bf16_f32 v192, v100, v101
	v_cvt_pk_bf16_f32 v193, v102, v103
	v_cvt_pk_bf16_f32 v194, v96, v97
	v_cvt_pk_bf16_f32 v195, v98, v99
	s_nop 1
	v_permlane32_swap_b32_e32 v188, v192
	v_permlane32_swap_b32_e32 v189, v193
	v_permlane32_swap_b32_e32 v190, v194
	v_permlane32_swap_b32_e32 v191, v195
	s_nop 0
	v_permlane16_swap_b32_e32 v188, v190
	v_permlane16_swap_b32_e32 v189, v191
	v_permlane16_swap_b32_e32 v192, v194
	v_permlane16_swap_b32_e32 v193, v195
	s_nop 1
	global_store_dwordx4 v204, v[188:191], s[10:11]
	global_store_dwordx4 v204, v[192:195], s[10:11] offset:16
	s_add_u32 s10, s76, 0x80000
	s_addc_u32 s11, s77, 0
	v_cvt_pk_bf16_f32 v148, v92, v93
	v_cvt_pk_bf16_f32 v149, v94, v95
	v_cvt_pk_bf16_f32 v150, v88, v89
	v_cvt_pk_bf16_f32 v151, v90, v91
	v_cvt_pk_bf16_f32 v152, v84, v85
	v_cvt_pk_bf16_f32 v153, v86, v87
	v_cvt_pk_bf16_f32 v154, v80, v81
	v_cvt_pk_bf16_f32 v155, v82, v83
	s_nop 1
	v_permlane32_swap_b32_e32 v148, v152
	v_permlane32_swap_b32_e32 v149, v153
	v_permlane32_swap_b32_e32 v150, v154
	v_permlane32_swap_b32_e32 v151, v155
	s_nop 0
	v_permlane16_swap_b32_e32 v148, v150
	v_permlane16_swap_b32_e32 v149, v151
	v_permlane16_swap_b32_e32 v152, v154
	v_permlane16_swap_b32_e32 v153, v155
	s_nop 1
	global_store_dwordx4 v204, v[148:151], s[10:11]
	global_store_dwordx4 v204, v[152:155], s[10:11] offset:16
	s_add_u32 s10, s76, 0xc0000
	s_addc_u32 s11, s77, 0
	v_cvt_pk_bf16_f32 v188, v76, v77
	v_cvt_pk_bf16_f32 v189, v78, v79
	v_cvt_pk_bf16_f32 v190, v72, v73
	v_cvt_pk_bf16_f32 v191, v74, v75
	v_cvt_pk_bf16_f32 v192, v68, v69
	v_cvt_pk_bf16_f32 v193, v70, v71
	v_cvt_pk_bf16_f32 v194, v48, v49
	v_cvt_pk_bf16_f32 v195, v50, v51
	s_nop 1
	v_permlane32_swap_b32_e32 v188, v192
	v_permlane32_swap_b32_e32 v189, v193
	v_permlane32_swap_b32_e32 v190, v194
	v_permlane32_swap_b32_e32 v191, v195
	s_nop 0
	v_permlane16_swap_b32_e32 v188, v190
	v_permlane16_swap_b32_e32 v189, v191
	v_permlane16_swap_b32_e32 v192, v194
	v_permlane16_swap_b32_e32 v193, v195
	s_nop 1
	global_store_dwordx4 v204, v[188:191], s[10:11]
	global_store_dwordx4 v204, v[192:195], s[10:11] offset:16
	s_add_u32 s10, s76, 0x100000
	s_addc_u32 s11, s77, 0
	v_cvt_pk_bf16_f32 v148, v44, v45
	v_cvt_pk_bf16_f32 v149, v46, v47
	v_cvt_pk_bf16_f32 v150, v40, v41
	v_cvt_pk_bf16_f32 v151, v42, v43
	v_cvt_pk_bf16_f32 v152, v36, v37
	v_cvt_pk_bf16_f32 v153, v38, v39
	v_cvt_pk_bf16_f32 v154, v32, v33
	v_cvt_pk_bf16_f32 v155, v34, v35
	s_nop 1
	v_permlane32_swap_b32_e32 v148, v152
	v_permlane32_swap_b32_e32 v149, v153
	v_permlane32_swap_b32_e32 v150, v154
	v_permlane32_swap_b32_e32 v151, v155
	s_nop 0
	v_permlane16_swap_b32_e32 v148, v150
	v_permlane16_swap_b32_e32 v149, v151
	v_permlane16_swap_b32_e32 v152, v154
	v_permlane16_swap_b32_e32 v153, v155
	s_nop 1
	global_store_dwordx4 v204, v[148:151], s[10:11]
	global_store_dwordx4 v204, v[152:155], s[10:11] offset:16
	s_add_u32 s10, s76, 0x140000
	s_addc_u32 s11, s77, 0
	v_cvt_pk_bf16_f32 v188, v28, v29
	v_cvt_pk_bf16_f32 v189, v30, v31
	v_cvt_pk_bf16_f32 v190, v24, v25
	v_cvt_pk_bf16_f32 v191, v26, v27
	v_cvt_pk_bf16_f32 v192, v20, v21
	v_cvt_pk_bf16_f32 v193, v22, v23
	v_cvt_pk_bf16_f32 v194, v16, v17
	v_cvt_pk_bf16_f32 v195, v18, v19
	s_nop 1
	v_permlane32_swap_b32_e32 v188, v192
	v_permlane32_swap_b32_e32 v189, v193
	v_permlane32_swap_b32_e32 v190, v194
	v_permlane32_swap_b32_e32 v191, v195
	s_nop 0
	v_permlane16_swap_b32_e32 v188, v190
	v_permlane16_swap_b32_e32 v189, v191
	v_permlane16_swap_b32_e32 v192, v194
	v_permlane16_swap_b32_e32 v193, v195
	s_nop 1
	global_store_dwordx4 v204, v[188:191], s[10:11]
	global_store_dwordx4 v204, v[192:195], s[10:11] offset:16
	s_add_u32 s10, s76, 0x180000
	s_addc_u32 s11, s77, 0
	v_cvt_pk_bf16_f32 v148, v12, v13
	v_cvt_pk_bf16_f32 v149, v14, v15
	v_cvt_pk_bf16_f32 v150, v8, v9
	v_cvt_pk_bf16_f32 v151, v10, v11
	v_cvt_pk_bf16_f32 v152, v4, v5
	v_cvt_pk_bf16_f32 v153, v6, v7
	v_cvt_pk_bf16_f32 v154, v0, v1
	v_cvt_pk_bf16_f32 v155, v2, v3
	s_nop 1
	v_permlane32_swap_b32_e32 v148, v152
	v_permlane32_swap_b32_e32 v149, v153
	v_permlane32_swap_b32_e32 v150, v154
	v_permlane32_swap_b32_e32 v151, v155
	s_nop 0
	v_permlane16_swap_b32_e32 v148, v150
	v_permlane16_swap_b32_e32 v149, v151
	v_permlane16_swap_b32_e32 v152, v154
	v_permlane16_swap_b32_e32 v153, v155
	s_nop 1
	global_store_dwordx4 v204, v[148:151], s[10:11]
	global_store_dwordx4 v204, v[152:155], s[10:11] offset:16
	s_add_u32 s10, s76, 0x1c0000
	s_addc_u32 s11, s77, 0
	v_cvt_pk_bf16_f32 v188, v60, v61
	v_cvt_pk_bf16_f32 v189, v62, v63
	v_cvt_pk_bf16_f32 v190, v64, v65
	v_cvt_pk_bf16_f32 v191, v66, v67
	v_cvt_pk_bf16_f32 v192, v52, v53
	v_cvt_pk_bf16_f32 v193, v54, v55
	v_cvt_pk_bf16_f32 v194, v56, v57
	v_cvt_pk_bf16_f32 v195, v58, v59
	s_nop 1
	v_permlane32_swap_b32_e32 v188, v192
	v_permlane32_swap_b32_e32 v189, v193
	v_permlane32_swap_b32_e32 v190, v194
	v_permlane32_swap_b32_e32 v191, v195
	s_nop 0
	v_permlane16_swap_b32_e32 v188, v190
	v_permlane16_swap_b32_e32 v189, v191
	v_permlane16_swap_b32_e32 v192, v194
	v_permlane16_swap_b32_e32 v193, v195
	s_nop 1
	global_store_dwordx4 v204, v[188:191], s[10:11]
	global_store_dwordx4 v204, v[192:195], s[10:11] offset:16
	s_branch .LBB1_1174
